# GEMM1 tail fill: short blocks take up to 7 weight-transposes tiles instead of 10
# baseline (speedup 1.0000x reference)
.LBB0_441:
	s_barrier
	s_and_saveexec_b64 s[2:3], vcc
	s_cbranch_execz .LBB0_447
	s_cmp_gt_u32 s10, 6
	v_mov_b32_e32 v136, 0x670
	s_cbranch_scc1 .LBB0_446
	s_mov_b64 s[18:19], exec
	v_mbcnt_lo_u32_b32 v136, s18, 0
	v_mbcnt_hi_u32_b32 v136, s19, v136
	v_cmp_eq_u32_e64 s[0:1], 0, v136
	s_and_saveexec_b64 s[4:5], s[0:1]
	s_cbranch_execz .LBB0_445
	s_bcnt1_i32_b64 s0, s[18:19]
	v_mov_b32_e32 v137, s0
	global_atomic_add v137, v135, v137, s[6:7] sc0
